# v51 + all four ffn_out GEMMs: latent tile order transposed within each XCD's 8-panel group (4 panels x 8 column tiles per round, ACT panels streamed once instead of once per round)
# speedup vs baseline: 1.0099x; 1.0090x over previous
;     __device__ __forceinline__ unsigned code(int i, unsigned& ko_) const { Unit u; u.pm = 0; u.pn = 0; u.ko = 0; u.nk = 0; u.ks = 0; const bool ok = next(i, u); ko_ = (unsigned)u.ko; return ok ? (0x80000000u | ((unsigned)u.nk << 16) | ((unsigned)u.pm << 8) | (unsigned)u.pn) : 0u; }
;     __host__ __device__ __forceinline__ bool next(int i, Unit& u) const {
;         const long L = (long)i * G + c; if (L >= nwg) return false;
;         int wgid = (int)L; { const int q = nwg / NXCD, r = nwg % NXCD, xcd = wgid % NXCD, off = wgid / NXCD; wgid = (xcd < r ? xcd * (q + 1) : r * (q + 1) + (xcd - r) * q) + off; }
;         const int nig = WGM * nN, gid = wgid / nig, fm = gid * WGM, gsz = (nM - fm) < WGM ? (nM - fm) : WGM;
;         u.pm = fm + ((wgid % nig) % gsz); u.pn = (wgid % nig) / gsz; u.ko = 0; u.nk = nk; return true;
;     }
;         const int pair = (K / 64) / (nks_ / 2); t1 = ((pair / 2 + 1) / 2) * 2; t2 = pair - t1; }
;     __device__ __forceinline__ unsigned code(int i, unsigned& ko_) const {
;         const int L = i * lat.G + lat.c; if (L < nlat) return lat.code(i, ko_);
;         const int Lp = L - nlat; if (Lp >= nsp) { ko_ = 0u; return 0u; }
;         const int r = Lp / nks, ks = Lp % nks; ko_ = (unsigned)(((ks >> 1) * (t1 + t2) + (ks & 1) * t1) * 64);
;         return 0x80000000u | ((unsigned)ks << 24) | ((unsigned)((ks & 1) ? t2 : t1) << 16) | ((unsigned)(64 + (r & 3)) << 8) | (unsigned)(r >> 2);
;     }
.LBB0_250:
	s_or_b64 exec, exec, s[36:37]
	s_cmpk_lt_i32 s92, 0xbb0
	s_cselect_b64 s[0:1], -1, 0
	v_writelane_b32 v254, s0, 6
	s_ashr_i32 s90, s92, 31
	s_bfe_u32 s2, s92, 0x20001
	v_writelane_b32 v254, s1, 7
	s_lshr_b32 s0, s90, 29
	s_and_b32 s3, s92, 1
	s_add_i32 s0, s92, s0
	s_mul_i32 s2, s2, 22
	s_mul_i32 s4, s3, 12
	s_ashr_i32 s17, s0, 3
	s_and_b32 s0, s0, -8
	s_and_b32 s1, s92, 7
	s_add_i32 s2, s2, s4
	s_sub_i32 s18, s92, s0
	s_and_b32 s0, s92, 0x7fffff00
	s_lshl_b32 s2, s2, 6
	s_lshl_b32 s1, s1, 24
	s_cmp_eq_u32 s3, 0
	s_mov_b32 s3, 0xc0000
	s_cselect_b32 s3, s3, 0xa0000
	s_lshl_b32 s4, s92, 5
	s_and_b32 s4, s4, 0x300
	s_bfe_u32 s5, s92, 0x30005
	s_or_b32 s4, s5, s4
	s_or_b32 s1, s4, s1
	s_or_b32 s3, s1, s3
	s_or_b32 s3, s3, 0x80004000
	s_lshl_b32 s4, s18, 6
	s_lshl_b32 s6, s92, 9
	s_lshl_b32 s5, s92, 2
	s_cmpk_lt_i32 s5, 0x400
	v_writelane_b32 v254, s5, 8
	s_cselect_b64 s[8:9], -1, 0
	v_writelane_b32 v254, s8, 9
	s_lshl_b32 s7, s92, 24
	s_and_b32 s7, s7, 0x3000000
	v_writelane_b32 v254, s9, 10
	s_lshl_b32 s8, s92, 6
	s_bfe_u32 s10, s92, 0x40004
	s_and_b32 s9, s8, 0x300
	s_or_b32 s7, s7, s10
	s_or_b32 s7, s7, s9
	s_add_i32 s5, s92, 0xfffffd00
	v_writelane_b32 v254, s6, 11
	s_and_b32 s6, s6, 0x600
	s_or_b32 s7, s7, 0x80084000
	s_cmpk_lt_i32 s92, 0xcc
	s_cselect_b64 s[10:11], -1, 0
	s_lshl_b32 s12, s94, 8
	s_add_i32 s59, s12, 0
	s_lshl_b32 s12, s94, 12
	v_writelane_b32 v254, s10, 12
	s_add_i32 s12, s12, 0
	s_add_i32 s12, s12, 0x14800
	v_writelane_b32 v254, s11, 13
	v_writelane_b32 v254, s12, 14
	s_add_i32 s12, s92, 0xfffffe00
	s_mul_i32 s9, s18, 25
	v_writelane_b32 v254, s12, 15
	s_lshl_b32 s12, s92, 8
	s_add_i32 s9, s9, 4
	s_add_i32 s10, s92, 0xcc
	s_add_i32 s11, s92, 0xdc
	s_add_i32 s95, s59, 0x10000
	s_lshl_b32 s19, s94, 5
	s_add_i32 s59, s59, 0x14000
	s_and_b32 s12, s12, 0x700
	s_or_b32 s1, s1, 0x80044000
	v_writelane_b32 v254, s12, 16
	s_cmp_lt_i32 s18, 0
	s_movk_i32 s12, 0x177
	v_writelane_b32 v254, s1, 17
	s_mul_i32 s1, s18, 0x41
	s_cselect_b32 s12, s12, 0x176
	s_mul_i32 s12, s18, s12
	s_cselect_b32 s1, s1, s4
	s_movk_i32 s4, 0x61
	s_cselect_b32 s4, s4, 0x60
	s_add_i32 s12, s12, s17
	s_mul_hi_i32 s13, s12, 0x2e8ba2e9
	s_lshr_b32 s14, s13, 31
	s_ashr_i32 s13, s13, 6
	s_add_i32 s13, s13, s14
	s_mul_i32 s14, s13, 0x160
	s_lshl_b32 s13, s13, 3
	s_sub_i32 s15, 0x44, s13
	s_min_u32 s15, s15, 8
	s_sub_i32 s12, s12, s14
	s_cmpk_eq_i32 s0, 0x200
	s_cselect_b32 s2, s2, 0
	s_cselect_b32 s3, s3, 0
	s_add_i32 s0, s1, s17
	s_ashr_i32 s1, s0, 31
	s_lshr_b32 s1, s1, 26
	s_add_i32 s1, s0, s1
	s_and_b32 s14, s1, 0xffc0
	s_sub_i32 s0, s0, s14
	s_bfe_i32 s14, s0, 0x80000
	s_bfe_u32 s14, s14, 0x3000c
	s_add_i32 s14, s0, s14
	s_bfe_i32 s16, s14, 0x80000
	s_and_b32 s14, s14, 0xf8
	s_sub_i32 s0, s0, s14
	s_sext_i32_i8 s0, s0
	s_lshl_b32 s1, s1, 5
	s_sext_i32_i16 s16, s16
	s_and_b32 s1, s1, 0xfffff800
	s_lshl_b32 s0, s0, 8
	s_ashr_i32 s14, s16, 3
	s_add_i32 s0, s0, s1
	s_or_b32 s0, s0, s14
	s_or_b32 s14, s0, 0x80580000
	s_cmpk_lt_u32 s5, 0xc0
	s_mul_i32 s4, s18, s4
	s_cselect_b32 s1, s6, 0
	s_cselect_b32 s5, s7, 0
	s_add_i32 s4, s4, s17
	s_mul_hi_i32 s6, s4, 0x2aaaaaab
	s_lshr_b32 s7, s6, 31
	s_ashr_i32 s6, s6, 4
	s_add_i32 s6, s6, s7
	s_mul_i32 s7, s6, 0x60
	s_sub_i32 s4, s4, s7
	s_bfe_i32 s7, s4, 0x80000
	s_bfe_u32 s7, s7, 0x3000c
	s_add_i32 s7, s4, s7
	s_bfe_i32 s16, s7, 0x80000
	s_and_b32 s7, s7, 0xf8
	s_sub_i32 s4, s4, s7
	s_sext_i32_i8 s4, s4
	s_sext_i32_i16 s16, s16
	s_lshl_b32 s6, s6, 11
	s_lshl_b32 s4, s4, 8
	s_ashr_i32 s7, s16, 3
	s_add_i32 s4, s4, s6
	s_or_b32 s4, s4, s7
	s_or_b32 s4, s4, 0x80200000
	s_cmp_lt_i32 s18, 4
	s_mul_i32 s6, s18, 26
	s_cselect_b32 s6, s6, s9
	s_add_i32 s6, s6, s17
	s_mul_hi_i32 s7, s6, 0x2aaaaaab
	s_lshr_b32 s9, s7, 31
	s_ashr_i32 s7, s7, 2
	s_add_i32 s7, s7, s9
;     __host__ __device__ __forceinline__ bool next(int i, Unit& u) const {
;         const long L = (long)i * G + c; if (L >= nwg) return false;
;         int wgid = (int)L; { const int q = nwg / NXCD, r = nwg % NXCD, xcd = wgid % NXCD, off = wgid / NXCD; wgid = (xcd < r ? xcd * (q + 1) : r * (q + 1) + (xcd - r) * q) + off; }
;         const int nig = WGM * nN, gid = wgid / nig, fm = gid * WGM, gsz = (nM - fm) < WGM ? (nM - fm) : WGM;
;         u.pm = fm + ((wgid % nig) % gsz); u.pn = (wgid % nig) / gsz; u.ko = 0; u.nk = nk; return true;
;     }
	s_lshl_b32 s9, s7, 3
	s_sub_i32 s16, 0x44, s9
	s_mul_i32 s7, s7, 24
	s_min_u32 s16, s16, 8
	s_sub_i32 s6, s6, s7
	s_or_b32 s0, s0, 0x80200000
	v_writelane_b32 v254, s17, 18
	s_cmpk_lt_i32 s92, 0x300
	v_writelane_b32 v254, s0, 19
	s_cselect_b32 s0, 0, s1
	v_writelane_b32 v254, s0, 20
	v_cvt_f32_ubyte0_e32 v1, s15
	v_cvt_f32_i32_e32 v0, s12
	v_writelane_b32 v254, s1, 21
	s_cselect_b32 s0, s4, s5
	v_writelane_b32 v254, s0, 22
	v_writelane_b32 v254, s18, 23
	s_lshr_b32 s0, s18, 31
	v_writelane_b32 v254, s0, 24
	s_mul_i32 s4, s94, 0x21000
	v_writelane_b32 v254, s4, 25
	s_cmpk_lt_i32 s92, 0x200
	v_writelane_b32 v254, s19, 26
	s_mul_hi_u32 s4, s19, 0x1080
	s_cselect_b64 s[0:1], -1, 0
	v_writelane_b32 v254, s4, 27
	v_rcp_iflag_f32_e32 v2, v1
	v_writelane_b32 v254, s0, 28
	s_mov_b64 s[4:5], -1
	s_movk_i32 s73, 0x600
	v_writelane_b32 v254, s1, 29
	s_and_b64 s[0:1], s[0:1], exec
	s_cselect_b32 s0, 0, s2
	v_writelane_b32 v254, s0, 30
	v_mul_f32_e32 v2, v0, v2
	v_trunc_f32_e32 v2, v2
	v_writelane_b32 v254, s1, 31
	s_cselect_b32 s0, s14, s3
	v_writelane_b32 v254, s0, 32
	s_cselect_b32 s0, s14, 0
	v_fma_f32 v0, -v2, v1, v0
	v_cvt_i32_f32_e32 v2, v2
	v_writelane_b32 v254, s0, 33
	s_and_b32 s0, s92, 7
	s_lshl_b32 s0, s0, 3
	s_lshr_b32 s1, s92, 6
	s_add_i32 s0, s0, s1
	s_lshl_b32 s0, s0, 8
	s_bfe_u32 s1, s92, 0x30003
	s_or_b32 s0, s0, s1
	s_or_b32 s0, s0, 0x80580000
	v_writelane_b32 v254, s0, 32
	v_writelane_b32 v254, s0, 33
	s_ashr_i32 s0, s12, 30
	s_or_b32 s2, s0, 1
	v_cmp_ge_f32_e64 s[0:1], |v0|, v1
	s_and_b64 s[0:1], s[0:1], exec
	s_cselect_b32 s0, s2, 0
	v_readfirstlane_b32 s1, v2
	s_add_i32 s0, s1, s0
	v_cvt_f32_ubyte0_e32 v1, s16
	s_sext_i32_i16 s1, s0
	s_mul_i32 s0, s0, s15
	v_cvt_f32_i32_e32 v0, s6
	v_rcp_iflag_f32_e32 v2, v1
	s_sub_i32 s0, s12, s0
	s_sext_i32_i16 s0, s0
	s_add_i32 s13, s13, s0
	s_lshl_b32 s0, s13, 8
	v_mul_f32_e32 v2, v0, v2
	s_or_b32 s0, s0, s1
	v_trunc_f32_e32 v2, v2
	s_or_b32 s0, s0, 0x80200000
	v_fma_f32 v0, -v2, v1, v0
	v_cvt_i32_f32_e32 v2, v2
	v_writelane_b32 v254, s0, 34
	s_ashr_i32 s0, s6, 30
	s_or_b32 s2, s0, 1
	v_cmp_ge_f32_e64 s[0:1], |v0|, v1
	s_and_b64 s[0:1], s[0:1], exec
	s_cselect_b32 s0, s2, 0
	v_readfirstlane_b32 s1, v2
	s_add_i32 s0, s1, s0
	s_sext_i32_i8 s1, s0
	s_mul_i32 s0, s0, s16
	s_sub_i32 s0, s6, s0
	s_sext_i32_i8 s0, s0
	s_add_i32 s9, s9, s0
	s_lshl_b32 s0, s9, 8
	s_or_b32 s0, s0, s1
	s_or_b32 s0, s0, 0x80080000
	v_writelane_b32 v254, s0, 35
	s_ashr_i32 s0, s10, 31
	v_writelane_b32 v254, s0, 36
	s_abs_i32 s0, s10
	v_writelane_b32 v254, s0, 37
	s_ashr_i32 s0, s11, 31
	v_writelane_b32 v254, s0, 38
	s_abs_i32 s0, s11
	v_writelane_b32 v254, s0, 39
	s_or_b32 s0, s8, 7
	v_writelane_b32 v254, s0, 40
	s_add_i32 s0, 0, 0x25ff0
	v_writelane_b32 v254, s0, 41
	s_add_i32 s0, 0, 0x25ff4
	v_writelane_b32 v254, s0, 42
	s_mov_b32 s2, 0
	v_writelane_b32 v254, s2, 43
	v_writelane_b32 v254, s4, 45
	s_movk_i32 s3, 0x1800
	s_mov_b32 s2, s92
	v_writelane_b32 v254, s5, 46
	v_writelane_b32 v254, s96, 47
	s_movk_i32 s66, 0x1080
	v_mov_b32_e32 v193, 0
	v_writelane_b32 v254, s97, 48
	v_writelane_b32 v254, s2, 49
	v_mov_b32_e32 v243, 1
	v_mov_b32_e32 v241, 0x358637bd
	v_writelane_b32 v254, s3, 50
	v_writelane_b32 v254, s94, 51
	s_mov_b32 s68, 0x800000
	s_mov_b32 s79, 0xc00000
	s_movk_i32 s91, 0x1000
	s_mov_b32 s1, 0x42b504f3
	s_mov_b32 s0, 0x1c8ff000
	s_mov_b32 s67, 0x1c07f000
	s_mov_b32 s61, 0x1c907000
	s_mov_b32 s64, 0x1c087000
	s_mov_b32 s69, 0x42ddb3d8
	s_mov_b32 s38, 0x2048f000
	s_mov_b32 s39, 0x1eb1f000
	s_mov_b32 s63, 0x2049f000
	s_mov_b32 s82, 0x1eb37000
	s_mov_b64 s[74:75], 0x20000
	s_mov_b32 s76, 0x3e0293ee
	s_mov_b32 s78, 0x3dd53b94
	s_mov_b64 s[80:81], 0x30000
	s_mov_b32 s41, 0
	v_writelane_b32 v254, s90, 52
	s_waitcnt lgkmcnt(0)
	s_barrier
	s_branch .LBB0_254

;     __host__ __device__ __forceinline__ bool next(int i, Unit& u) const {
;     ...
;         int wgid = (int)L; { const int q = nwg / NXCD, r = nwg % NXCD, xcd = wgid % NXCD, off = wgid / NXCD; wgid = (xcd < r ? xcd * (q + 1) : r * (q + 1) + (xcd - r) * q) + off; }
;         const int nig = WGM * nN, gid = wgid / nig, fm = gid * WGM, gsz = (nM - fm) < WGM ? (nM - fm) : WGM;
;         u.pm = fm + ((wgid % nig) % gsz); u.pn = (wgid % nig) / gsz; u.ko = 0; u.nk = nk; return true;
.LBB0_390:
	s_ashr_i32 s2, s7, 3
	s_add_i32 s2, s28, s2
	s_ashr_i32 s7, s2, 31
	s_lshr_b32 s7, s7, 26
	s_add_i32 s7, s2, s7
	s_ashr_i32 s10, s7, 6
	s_lshl_b32 s10, s10, 3
	s_sub_i32 s11, 64, s10
	s_min_i32 s11, s11, 8
	s_abs_i32 s25, s11
	v_cvt_f32_u32_e32 v0, s25
	s_sub_i32 s27, 0, s25
	s_andn2_b32 s7, s7, 63
	s_sub_i32 s2, s2, s7
	v_rcp_iflag_f32_e32 v0, v0
	s_abs_i32 s7, s2
	s_xor_b32 s26, s2, s11
	s_ashr_i32 s26, s26, 31
	v_mul_f32_e32 v0, 0x4f7ffffe, v0
	v_cvt_u32_f32_e32 v0, v0
	s_nop 0
	v_readfirstlane_b32 s28, v0
	s_mul_i32 s27, s27, s28
	s_mul_hi_u32 s27, s28, s27
	s_add_i32 s28, s28, s27
	s_mul_hi_u32 s27, s7, s28
	s_mul_i32 s28, s27, s25
	s_sub_i32 s7, s7, s28
	s_add_i32 s29, s27, 1
	s_sub_i32 s28, s7, s25
	s_cmp_ge_u32 s7, s25
	s_cselect_b32 s27, s29, s27
	s_cselect_b32 s7, s28, s7
	s_add_i32 s28, s27, 1
	s_cmp_ge_u32 s7, s25
	s_cselect_b32 s7, s28, s27
	s_xor_b32 s7, s7, s26
	s_sub_i32 s7, s7, s26
	s_mul_i32 s11, s7, s11
	s_sub_i32 s2, s2, s11
	s_add_i32 s10, s10, s7
	s_lshl_b32 s10, s10, 8
	s_or_b32 s2, s2, s10
	s_or_b32 s7, s2, 0x80580000

;     __host__ __device__ __forceinline__ bool next(int i, Unit& u) const {
;     ...
;         int wgid = (int)L; { const int q = nwg / NXCD, r = nwg % NXCD, xcd = wgid % NXCD, off = wgid / NXCD; wgid = (xcd < r ? xcd * (q + 1) : r * (q + 1) + (xcd - r) * q) + off; }
;         const int nig = WGM * nN, gid = wgid / nig, fm = gid * WGM, gsz = (nM - fm) < WGM ? (nM - fm) : WGM;
;         u.pm = fm + ((wgid % nig) % gsz); u.pn = (wgid % nig) / gsz; u.ko = 0; u.nk = nk; return true;
.LBB0_1239:
	s_ashr_i32 s2, s16, 3
	s_add_i32 s2, s18, s2
	s_ashr_i32 s14, s2, 31
	s_lshr_b32 s14, s14, 26
	s_add_i32 s14, s2, s14
	s_ashr_i32 s15, s14, 6
	s_lshl_b32 s15, s15, 3
	s_sub_i32 s16, 64, s15
	s_min_i32 s16, s16, 8
	s_abs_i32 s17, s16
	v_cvt_f32_u32_e32 v0, s17
	s_sub_i32 s19, 0, s17
	s_andn2_b32 s14, s14, 63
	s_sub_i32 s2, s2, s14
	v_rcp_iflag_f32_e32 v0, v0
	s_abs_i32 s14, s2
	s_xor_b32 s18, s2, s16
	s_ashr_i32 s18, s18, 31
	v_mul_f32_e32 v0, 0x4f7ffffe, v0
	v_cvt_u32_f32_e32 v0, v0
	s_nop 0
	v_readfirstlane_b32 s24, v0
	s_mul_i32 s19, s19, s24
	s_mul_hi_u32 s19, s24, s19
	s_add_i32 s24, s24, s19
	s_mul_hi_u32 s19, s14, s24
	s_mul_i32 s24, s19, s17
	s_sub_i32 s14, s14, s24
	s_add_i32 s25, s19, 1
	s_sub_i32 s24, s14, s17
	s_cmp_ge_u32 s14, s17
	s_cselect_b32 s19, s25, s19
	s_cselect_b32 s14, s24, s14
	s_add_i32 s24, s19, 1
	s_cmp_ge_u32 s14, s17
	s_cselect_b32 s14, s24, s19
	s_xor_b32 s14, s14, s18
	s_sub_i32 s14, s14, s18
	s_mul_i32 s16, s14, s16
	s_sub_i32 s2, s2, s16
	s_add_i32 s15, s15, s14
	s_lshl_b32 s15, s15, 8
	s_or_b32 s2, s2, s15
	s_or_b32 s18, s2, 0x80580000

;     __host__ __device__ __forceinline__ bool next(int i, Unit& u) const {
;     ...
;         int wgid = (int)L; { const int q = nwg / NXCD, r = nwg % NXCD, xcd = wgid % NXCD, off = wgid / NXCD; wgid = (xcd < r ? xcd * (q + 1) : r * (q + 1) + (xcd - r) * q) + off; }
;         const int nig = WGM * nN, gid = wgid / nig, fm = gid * WGM, gsz = (nM - fm) < WGM ? (nM - fm) : WGM;
;         u.pm = fm + ((wgid % nig) % gsz); u.pn = (wgid % nig) / gsz; u.ko = 0; u.nk = nk; return true;
.LBB0_1330:
	s_ashr_i32 s2, s9, 3
	s_add_i32 s2, s28, s2
	s_ashr_i32 s9, s2, 31
	s_lshr_b32 s9, s9, 26
	s_add_i32 s9, s2, s9
	s_ashr_i32 s10, s9, 6
	s_lshl_b32 s10, s10, 3
	s_sub_i32 s11, 64, s10
	s_min_i32 s11, s11, 8
	s_abs_i32 s25, s11
	v_cvt_f32_u32_e32 v0, s25
	s_sub_i32 s27, 0, s25
	s_andn2_b32 s9, s9, 63
	s_sub_i32 s2, s2, s9
	v_rcp_iflag_f32_e32 v0, v0
	s_abs_i32 s9, s2
	s_xor_b32 s26, s2, s11
	s_ashr_i32 s26, s26, 31
	v_mul_f32_e32 v0, 0x4f7ffffe, v0
	v_cvt_u32_f32_e32 v0, v0
	s_nop 0
	v_readfirstlane_b32 s28, v0
	s_mul_i32 s27, s27, s28
	s_mul_hi_u32 s27, s28, s27
	s_add_i32 s28, s28, s27
	s_mul_hi_u32 s27, s9, s28
	s_mul_i32 s28, s27, s25
	s_sub_i32 s9, s9, s28
	s_add_i32 s29, s27, 1
	s_sub_i32 s28, s9, s25
	s_cmp_ge_u32 s9, s25
	s_cselect_b32 s27, s29, s27
	s_cselect_b32 s9, s28, s9
	s_add_i32 s28, s27, 1
	s_cmp_ge_u32 s9, s25
	s_cselect_b32 s9, s28, s27
	s_xor_b32 s9, s9, s26
	s_sub_i32 s9, s9, s26
	s_mul_i32 s11, s9, s11
	s_sub_i32 s2, s2, s11
	s_add_i32 s10, s10, s9
	s_lshl_b32 s10, s10, 8
	s_or_b32 s2, s2, s10
	s_or_b32 s9, s2, 0x80580000
